# gu supertile epilogue: DPP lane-pair packing into dword stores (half the store count)
# baseline (speedup 1.0000x reference)
; #define TIDX opaque_tid()
; #define GAS __attribute__((address_space(1)))
; DI int opaque0() { int z = 0; asm volatile("" : "+v"(z)); return z; }
; DI void gemm_tile_w(const u16* __restrict__ A, int lda, const u16* __restrict__ B, int ldb, int nk, bool swap,
;                     f32x16 (&acc)[2][4], char* lds) {
;   const int tid = TIDX, lane = tid & 63, wid = tid >> 6;
;   gemm_stage_w(A, lda, B, ldb, lds, tid);
;   asm volatile("s_waitcnt vmcnt(0)" ::: "memory");
;   __syncthreads();
;   const int r = lane & 31, h = lane >> 5, sw = (r >> 2) & 3;
;   const int wa = swap ? wid : (wid >> 1), wb = swap ? 0 : (wid & 1);
;   const int offF = (swap ? 8192 : 0) + (wa * 64 + r) * 64;
;   const int offS = (swap ? 0 : 8192) + (wb * 128 + r) * 64;
; template <int AI>
; DI void gu_tile(char* wsb, int sub, int m0, int n0, char* lds) {
;     ...
;   const int m0e = m0 + opaque0();
;   const int hc = (n0 >> 1) + wb * 32 + r;
;   GAS u16* HIDu = uptr(HID);
;   const unsigned ib = (unsigned)((m0e + wa * 32 * AI + 4 * h) * 2816 + hc);
.LBB0_417:
	s_or_b64 exec, exec, s[6:7]
	s_mov_b32 s6, s19
	s_mov_b64 s[8:9], s[20:21]
	s_waitcnt lgkmcnt(0)
	s_barrier
	s_mov_b64 s[14:15], s[26:27]
	s_add_u32 s8, s14, s6
	v_readlane_b32 s6, v244, 48
	v_readlane_b32 s7, v244, 49
	s_mov_b64 s[10:11], s[22:23]
	s_addc_u32 s9, s15, 0
	v_cndmask_b32_e64 v0, 0, 1, s[6:7]
	v_cmp_ne_u32_e64 s[10:11], 1, v0
	s_andn2_b64 vcc, exec, s[6:7]
	s_mov_b64 s[12:13], s[24:25]
	v_writelane_b32 v242, s10, 3
	s_nop 1
	v_writelane_b32 v242, s11, 4
	s_cbranch_vccnz .LBB0_421
	s_add_u32 s10, s8, 0x77b7000
	s_addc_u32 s11, s9, 0
	s_add_u32 s12, s8, 0x1c4b7000
	s_addc_u32 s13, s9, 0
	s_add_u32 s6, s8, 0x9bb7000
	s_addc_u32 s7, s9, 0
	v_readlane_b32 s14, v243, 18
	v_readlane_b32 s15, v243, 5
	v_readlane_b32 s53, v243, 7
	s_mov_b32 s54, 0x1ffffc0
	s_mov_b64 s[70:71], 0x300
	s_mov_b64 s[72:73], 0x380
	s_mov_b64 s[74:75], 0x400
	s_mov_b64 s[76:77], 0x480
	s_mov_b64 s[80:81], 0x500
	s_mov_b64 s[82:83], 0x580
	s_mov_b64 s[84:85], 0x600
	s_mov_b64 s[56:57], 0x200
	s_mov_b64 s[64:65], 0x80
	s_mov_b64 s[66:67], 0x180
	s_mov_b64 s[68:69], 0x280
	s_cmpk_lg_u32 s92, 0x200
	s_cbranch_scc1 .LBB0_419
	v_and_b32_e32 v0, 31, v178
	v_bfe_u32 v122, v178, 5, 1
	v_bfe_u32 v123, v178, 2, 2
	v_xor_b32_e32 v122, v122, v123
	v_lshlrev_b32_e32 v122, 4, v122
	v_bfe_u32 v123, v178, 7, 1
	v_lshl_add_u32 v123, v123, 6, v0
	v_lshl_add_u32 v142, v123, 6, v122
	v_xor_b32_e32 v143, 32, v142
	v_bfe_u32 v123, v178, 6, 1
	v_lshl_add_u32 v123, v123, 6, v0
	v_lshl_add_u32 v144, v123, 6, v122
	v_add_u32_e32 v144, 0xc000, v144
	v_xor_b32_e32 v145, 32, v144
	v_bfe_u32 v122, v178, 7, 1
	v_lshlrev_b32_e32 v122, 6, v122
	v_bfe_u32 v123, v178, 5, 1
	v_lshl_add_u32 v122, v123, 2, v122
	v_mul_u32_u24_e32 v122, 0xb00, v122
	v_bfe_u32 v123, v178, 6, 1
	v_lshl_add_u32 v123, v123, 5, v0
	v_add_u32_e32 v122, v122, v123
	v_lshlrev_b32_e32 v124, 1, v122
	v_lshrrev_b32_e32 v0, 2, v178
	v_bfe_u32 v122, v178, 4, 2
	v_and_b32_e32 v123, 3, v178
	v_xor_b32_e32 v122, v122, v123
	v_lshlrev_b32_e32 v122, 4, v122
	v_lshl_add_u32 v126, v0, 11, v122
	v_add_u32_e32 v127, 0x20000, v126
	v_add_u32_e32 v128, 0x40000, v126
	v_add_u32_e32 v129, 0x60000, v126
	v_lshrrev_b32_e32 v0, 6, v178
	s_nop 1
	v_readfirstlane_b32 s18, v0
	s_lshl_b32 s18, s18, 10
	s_and_b32 s41, s96, 7
	s_lshr_b32 s40, s96, 3
	s_mov_b32 s32, 0
	s_mov_b32 s46, 0x55555555
	s_mov_b32 s47, 0x55555555
	v_and_b32_e32 v123, 1, v178
	v_mul_u32_u24_e32 v123, 0x15fe, v123
	v_add_u32_e32 v123, v123, v124

; #define MFMA(a, b, c) __builtin_amdgcn_mfma_f32_32x32x16_bf16((a), (b), (c), 0, 0, 0)
; #define TIDX opaque_tid()
; DI void gemm_stage_w(const u16* __restrict__ A, int lda, const u16* __restrict__ B, int ldb, char* buf, int tid) {
; #pragma unroll
;   for (int i = 0; i < 2; ++i) {
;     const int S = tid + NTHR * i, row = S >> 2, c = (S & 3) ^ ((row >> 2) & 3);
;     __builtin_amdgcn_global_load_lds((const unsigned*)(A + (size_t)row * lda + c * 8), (__attribute__((address_space(3))) unsigned*)(buf + S * 16), 16, 0, 0);
;   }
; #pragma unroll
;   for (int i = 0; i < 4; ++i) {
;     const int S = tid + NTHR * i, row = S >> 2, c = (S & 3) ^ ((row >> 2) & 3);
;     __builtin_amdgcn_global_load_lds((const unsigned*)(B + (size_t)row * ldb + c * 8), (__attribute__((address_space(3))) unsigned*)(buf + 8192 + S * 16), 16, 0, 0);
;   }
; }
; DI void gemm_tile_w(const u16* __restrict__ A, int lda, const u16* __restrict__ B, int ldb, int nk, bool swap,
;                     f32x16 (&acc)[2][4], char* lds) {
;   const int tid = TIDX, lane = tid & 63, wid = tid >> 6;
;   gemm_stage_w(A, lda, B, ldb, lds, tid);
;   asm volatile("s_waitcnt vmcnt(0)" ::: "memory");
;   __syncthreads();
;   const int r = lane & 31, h = lane >> 5, sw = (r >> 2) & 3;
;   const int wa = swap ? wid : (wid >> 1), wb = swap ? 0 : (wid & 1);
;   const int offF = (swap ? 8192 : 0) + (wa * 64 + r) * 64;
;   const int offS = (swap ? 0 : 8192) + (wb * 128 + r) * 64;
;   for (int kt = 0; kt < nk; ++kt) {
;     const char* cur = lds + (kt & 1) * 24576;
;     if (kt + 1 < nk) gemm_stage_w(A + (kt + 1) * 32, lda, B + (kt + 1) * 32, ldb, lds + ((kt + 1) & 1) * 24576, tid);
; #pragma unroll
;     for (int ks = 0; ks < 2; ++ks) {
;       const int co = ((ks * 2 + h) ^ sw) << 4;
;       s16x8 f0 = *(const s16x8*)(cur + offF + co), f1 = *(const s16x8*)(cur + offF + 2048 + co);
; #pragma unroll
;       for (int si = 0; si < 4; ++si) {
;         s16x8 sb = *(const s16x8*)(cur + offS + si * 2048 + co);
;         acc[0][si] = MFMA(f0, sb, acc[0][si]);
;         acc[1][si] = MFMA(f1, sb, acc[1][si]);
;       }
;     }
;     asm volatile("s_waitcnt vmcnt(0)" ::: "memory");
;     __syncthreads();
;   }
; }
.Lgu1_kloop:
	s_waitcnt vmcnt(6)
	s_barrier
	ds_read_b128 v[114:117], v142 offset:0
	ds_read_b128 v[230:233], v144 offset:0
	ds_read_b128 v[234:237], v144 offset:2048
	ds_read_b128 v[118:121], v142 offset:2048
	ds_read_b128 v[134:137], v142 offset:8192
	ds_read_b128 v[138:141], v142 offset:10240
	ds_read_b128 v[238:241], v145 offset:0
	ds_read_b128 v[246:249], v145 offset:2048
	s_add_u32 m0, s18, 32768
	s_nop 0
	global_load_lds_dwordx4 v126, s[16:17]
	s_add_u32 m0, s18, 36864
	s_nop 0
	global_load_lds_dwordx4 v127, s[16:17]
	s_add_u32 m0, s18, 40960
	s_nop 0
	global_load_lds_dwordx4 v128, s[16:17]
	s_add_u32 m0, s18, 45056
	s_nop 0
	global_load_lds_dwordx4 v129, s[16:17]
	s_add_u32 m0, s18, 65664
	s_nop 0
	global_load_lds_dwordx4 v126, s[28:29]
	s_add_u32 m0, s18, 69760
	s_nop 0
	global_load_lds_dwordx4 v127, s[28:29]
	s_add_u32 s16, s16, 64
	s_addc_u32 s17, s17, 0
	s_add_u32 s28, s28, 64
	s_addc_u32 s29, s29, 0
	s_waitcnt lgkmcnt(6)
	v_mfma_f32_32x32x16_bf16 v[2:17], v[114:117], v[230:233], v[2:17]
	s_waitcnt lgkmcnt(5)
	v_mfma_f32_32x32x16_bf16 v[18:33], v[114:117], v[234:237], v[18:33]
	ds_read_b128 v[114:117], v143 offset:0
	s_waitcnt lgkmcnt(5)
	v_mfma_f32_32x32x16_bf16 v[34:49], v[118:121], v[230:233], v[34:49]
	v_mfma_f32_32x32x16_bf16 v[50:65], v[118:121], v[234:237], v[50:65]
	ds_read_b128 v[118:121], v143 offset:2048
	s_waitcnt lgkmcnt(5)
	v_mfma_f32_32x32x16_bf16 v[66:81], v[134:137], v[230:233], v[66:81]
	v_mfma_f32_32x32x16_bf16 v[82:97], v[134:137], v[234:237], v[82:97]
	ds_read_b128 v[134:137], v143 offset:8192
	s_waitcnt lgkmcnt(5)
	v_mfma_f32_32x32x16_bf16 v[98:113], v[138:141], v[230:233], v[98:113]
	v_mfma_f32_32x32x16_bf16 v[214:229], v[138:141], v[234:237], v[214:229]
	ds_read_b128 v[138:141], v143 offset:10240
	s_waitcnt lgkmcnt(3)
	v_mfma_f32_32x32x16_bf16 v[2:17], v[114:117], v[238:241], v[2:17]
	v_mfma_f32_32x32x16_bf16 v[18:33], v[114:117], v[246:249], v[18:33]
	s_waitcnt lgkmcnt(2)
	v_mfma_f32_32x32x16_bf16 v[34:49], v[118:121], v[238:241], v[34:49]
	v_mfma_f32_32x32x16_bf16 v[50:65], v[118:121], v[246:249], v[50:65]
	s_waitcnt lgkmcnt(1)
	v_mfma_f32_32x32x16_bf16 v[66:81], v[134:137], v[238:241], v[66:81]
	v_mfma_f32_32x32x16_bf16 v[82:97], v[134:137], v[246:249], v[82:97]
	s_waitcnt lgkmcnt(0)
	v_mfma_f32_32x32x16_bf16 v[98:113], v[138:141], v[238:241], v[98:113]
	v_mfma_f32_32x32x16_bf16 v[214:229], v[138:141], v[246:249], v[214:229]
	s_waitcnt vmcnt(6)
	s_barrier
	ds_read_b128 v[114:117], v142 offset:16384
	ds_read_b128 v[230:233], v144 offset:8192
	ds_read_b128 v[234:237], v144 offset:10240
	ds_read_b128 v[118:121], v142 offset:18432
	ds_read_b128 v[134:137], v142 offset:24576
	ds_read_b128 v[138:141], v142 offset:26624
	ds_read_b128 v[238:241], v145 offset:8192
	ds_read_b128 v[246:249], v145 offset:10240
	s_add_u32 m0, s18, 0
	s_nop 0
	global_load_lds_dwordx4 v126, s[16:17]
	s_add_u32 m0, s18, 4096
	s_nop 0
	global_load_lds_dwordx4 v127, s[16:17]
	s_add_u32 m0, s18, 8192
	s_nop 0
	global_load_lds_dwordx4 v128, s[16:17]
	s_add_u32 m0, s18, 12288
	s_nop 0
	global_load_lds_dwordx4 v129, s[16:17]
	s_add_u32 m0, s18, 49152
	s_nop 0
	global_load_lds_dwordx4 v126, s[28:29]
	s_add_u32 m0, s18, 53248
	s_nop 0
	global_load_lds_dwordx4 v127, s[28:29]
	s_add_u32 s16, s16, 64
	s_addc_u32 s17, s17, 0
	s_add_u32 s28, s28, 64
	s_addc_u32 s29, s29, 0
	s_waitcnt lgkmcnt(6)
	v_mfma_f32_32x32x16_bf16 v[2:17], v[114:117], v[230:233], v[2:17]
	s_waitcnt lgkmcnt(5)
	v_mfma_f32_32x32x16_bf16 v[18:33], v[114:117], v[234:237], v[18:33]
	ds_read_b128 v[114:117], v143 offset:16384
	s_waitcnt lgkmcnt(5)
	v_mfma_f32_32x32x16_bf16 v[34:49], v[118:121], v[230:233], v[34:49]
	v_mfma_f32_32x32x16_bf16 v[50:65], v[118:121], v[234:237], v[50:65]
	ds_read_b128 v[118:121], v143 offset:18432
	s_waitcnt lgkmcnt(5)
	v_mfma_f32_32x32x16_bf16 v[66:81], v[134:137], v[230:233], v[66:81]
	v_mfma_f32_32x32x16_bf16 v[82:97], v[134:137], v[234:237], v[82:97]
	ds_read_b128 v[134:137], v143 offset:24576
	s_waitcnt lgkmcnt(5)
	v_mfma_f32_32x32x16_bf16 v[98:113], v[138:141], v[230:233], v[98:113]
	v_mfma_f32_32x32x16_bf16 v[214:229], v[138:141], v[234:237], v[214:229]
	ds_read_b128 v[138:141], v143 offset:26624
	s_waitcnt lgkmcnt(3)
	v_mfma_f32_32x32x16_bf16 v[2:17], v[114:117], v[238:241], v[2:17]
	v_mfma_f32_32x32x16_bf16 v[18:33], v[114:117], v[246:249], v[18:33]
	s_waitcnt lgkmcnt(2)
	v_mfma_f32_32x32x16_bf16 v[34:49], v[118:121], v[238:241], v[34:49]
	v_mfma_f32_32x32x16_bf16 v[50:65], v[118:121], v[246:249], v[50:65]
	s_waitcnt lgkmcnt(1)
	v_mfma_f32_32x32x16_bf16 v[66:81], v[134:137], v[238:241], v[66:81]
	v_mfma_f32_32x32x16_bf16 v[82:97], v[134:137], v[246:249], v[82:97]
	s_waitcnt lgkmcnt(0)
	v_mfma_f32_32x32x16_bf16 v[98:113], v[138:141], v[238:241], v[98:113]
	v_mfma_f32_32x32x16_bf16 v[214:229], v[138:141], v[246:249], v[214:229]
	s_waitcnt vmcnt(6)
	s_barrier
; #define MFMA(a, b, c) __builtin_amdgcn_mfma_f32_32x32x16_bf16((a), (b), (c), 0, 0, 0)
; #define TIDX opaque_tid()
; DI void gemm_stage_w(const u16* __restrict__ A, int lda, const u16* __restrict__ B, int ldb, char* buf, int tid) {
; #pragma unroll
;   for (int i = 0; i < 2; ++i) {
;     const int S = tid + NTHR * i, row = S >> 2, c = (S & 3) ^ ((row >> 2) & 3);
;     __builtin_amdgcn_global_load_lds((const unsigned*)(A + (size_t)row * lda + c * 8), (__attribute__((address_space(3))) unsigned*)(buf + S * 16), 16, 0, 0);
;   }
; #pragma unroll
;   for (int i = 0; i < 4; ++i) {
;     const int S = tid + NTHR * i, row = S >> 2, c = (S & 3) ^ ((row >> 2) & 3);
;     __builtin_amdgcn_global_load_lds((const unsigned*)(B + (size_t)row * ldb + c * 8), (__attribute__((address_space(3))) unsigned*)(buf + 8192 + S * 16), 16, 0, 0);
;   }
; }
; DI void gemm_tile_w(const u16* __restrict__ A, int lda, const u16* __restrict__ B, int ldb, int nk, bool swap,
;                     f32x16 (&acc)[2][4], char* lds) {
;   const int tid = TIDX, lane = tid & 63, wid = tid >> 6;
;   gemm_stage_w(A, lda, B, ldb, lds, tid);
;   asm volatile("s_waitcnt vmcnt(0)" ::: "memory");
;   __syncthreads();
;   const int r = lane & 31, h = lane >> 5, sw = (r >> 2) & 3;
;   const int wa = swap ? wid : (wid >> 1), wb = swap ? 0 : (wid & 1);
;   const int offF = (swap ? 8192 : 0) + (wa * 64 + r) * 64;
;   const int offS = (swap ? 0 : 8192) + (wb * 128 + r) * 64;
;   for (int kt = 0; kt < nk; ++kt) {
;     const char* cur = lds + (kt & 1) * 24576;
;     if (kt + 1 < nk) gemm_stage_w(A + (kt + 1) * 32, lda, B + (kt + 1) * 32, ldb, lds + ((kt + 1) & 1) * 24576, tid);
; #pragma unroll
;     for (int ks = 0; ks < 2; ++ks) {
;       const int co = ((ks * 2 + h) ^ sw) << 4;
;       s16x8 f0 = *(const s16x8*)(cur + offF + co), f1 = *(const s16x8*)(cur + offF + 2048 + co);
; #pragma unroll
;       for (int si = 0; si < 4; ++si) {
;         s16x8 sb = *(const s16x8*)(cur + offS + si * 2048 + co);
;         acc[0][si] = MFMA(f0, sb, acc[0][si]);
;         acc[1][si] = MFMA(f1, sb, acc[1][si]);
;       }
;     }
;     asm volatile("s_waitcnt vmcnt(0)" ::: "memory");
;     __syncthreads();
;   }
; }
	ds_read_b128 v[114:117], v142 offset:32768
	ds_read_b128 v[230:233], v144 offset:16512
	ds_read_b128 v[234:237], v144 offset:18560
	ds_read_b128 v[118:121], v142 offset:34816
	ds_read_b128 v[134:137], v142 offset:40960
	ds_read_b128 v[138:141], v142 offset:43008
	ds_read_b128 v[238:241], v145 offset:16512
	ds_read_b128 v[246:249], v145 offset:18560
	s_add_u32 m0, s18, 16384
	s_nop 0
	global_load_lds_dwordx4 v126, s[16:17]
	s_add_u32 m0, s18, 20480
	s_nop 0
	global_load_lds_dwordx4 v127, s[16:17]
	s_add_u32 m0, s18, 24576
	s_nop 0
	global_load_lds_dwordx4 v128, s[16:17]
	s_add_u32 m0, s18, 28672
	s_nop 0
	global_load_lds_dwordx4 v129, s[16:17]
	s_add_u32 m0, s18, 57344
	s_nop 0
	global_load_lds_dwordx4 v126, s[28:29]
	s_add_u32 m0, s18, 61440
	s_nop 0
	global_load_lds_dwordx4 v127, s[28:29]
	s_add_u32 s16, s16, 64
	s_addc_u32 s17, s17, 0
	s_add_u32 s28, s28, 64
	s_addc_u32 s29, s29, 0
	s_waitcnt lgkmcnt(6)
	v_mfma_f32_32x32x16_bf16 v[2:17], v[114:117], v[230:233], v[2:17]
	s_waitcnt lgkmcnt(5)
	v_mfma_f32_32x32x16_bf16 v[18:33], v[114:117], v[234:237], v[18:33]
	ds_read_b128 v[114:117], v143 offset:32768
	s_waitcnt lgkmcnt(5)
	v_mfma_f32_32x32x16_bf16 v[34:49], v[118:121], v[230:233], v[34:49]
	v_mfma_f32_32x32x16_bf16 v[50:65], v[118:121], v[234:237], v[50:65]
	ds_read_b128 v[118:121], v143 offset:34816
	s_waitcnt lgkmcnt(5)
	v_mfma_f32_32x32x16_bf16 v[66:81], v[134:137], v[230:233], v[66:81]
	v_mfma_f32_32x32x16_bf16 v[82:97], v[134:137], v[234:237], v[82:97]
	ds_read_b128 v[134:137], v143 offset:40960
	s_waitcnt lgkmcnt(5)
	v_mfma_f32_32x32x16_bf16 v[98:113], v[138:141], v[230:233], v[98:113]
	v_mfma_f32_32x32x16_bf16 v[214:229], v[138:141], v[234:237], v[214:229]
	ds_read_b128 v[138:141], v143 offset:43008
	s_waitcnt lgkmcnt(3)
	v_mfma_f32_32x32x16_bf16 v[2:17], v[114:117], v[238:241], v[2:17]
	v_mfma_f32_32x32x16_bf16 v[18:33], v[114:117], v[246:249], v[18:33]
	s_waitcnt lgkmcnt(2)
	v_mfma_f32_32x32x16_bf16 v[34:49], v[118:121], v[238:241], v[34:49]
	v_mfma_f32_32x32x16_bf16 v[50:65], v[118:121], v[246:249], v[50:65]
	s_waitcnt lgkmcnt(1)
	v_mfma_f32_32x32x16_bf16 v[66:81], v[134:137], v[238:241], v[66:81]
	v_mfma_f32_32x32x16_bf16 v[82:97], v[134:137], v[246:249], v[82:97]
	s_waitcnt lgkmcnt(0)
	v_mfma_f32_32x32x16_bf16 v[98:113], v[138:141], v[238:241], v[98:113]
	v_mfma_f32_32x32x16_bf16 v[214:229], v[138:141], v[246:249], v[214:229]
	s_sub_u32 s36, s36, 1
	s_cmp_lg_u32 s36, 0
	s_cbranch_scc1 .Lgu1_kloop
	s_waitcnt vmcnt(6)
	s_barrier
	ds_read_b128 v[114:117], v142 offset:0
	ds_read_b128 v[230:233], v144 offset:0
	ds_read_b128 v[234:237], v144 offset:2048
	ds_read_b128 v[118:121], v142 offset:2048
	ds_read_b128 v[134:137], v142 offset:8192
	ds_read_b128 v[138:141], v142 offset:10240
	ds_read_b128 v[238:241], v145 offset:0
	ds_read_b128 v[246:249], v145 offset:2048
	s_waitcnt lgkmcnt(6)
	v_mfma_f32_32x32x16_bf16 v[2:17], v[114:117], v[230:233], v[2:17]
	s_waitcnt lgkmcnt(5)
	v_mfma_f32_32x32x16_bf16 v[18:33], v[114:117], v[234:237], v[18:33]
	ds_read_b128 v[114:117], v143 offset:0
	s_waitcnt lgkmcnt(5)
	v_mfma_f32_32x32x16_bf16 v[34:49], v[118:121], v[230:233], v[34:49]
	v_mfma_f32_32x32x16_bf16 v[50:65], v[118:121], v[234:237], v[50:65]
	ds_read_b128 v[118:121], v143 offset:2048
	s_waitcnt lgkmcnt(5)
	v_mfma_f32_32x32x16_bf16 v[66:81], v[134:137], v[230:233], v[66:81]
	v_mfma_f32_32x32x16_bf16 v[82:97], v[134:137], v[234:237], v[82:97]
	ds_read_b128 v[134:137], v143 offset:8192
	s_waitcnt lgkmcnt(5)
	v_mfma_f32_32x32x16_bf16 v[98:113], v[138:141], v[230:233], v[98:113]
	v_mfma_f32_32x32x16_bf16 v[214:229], v[138:141], v[234:237], v[214:229]
	ds_read_b128 v[138:141], v143 offset:10240
	s_waitcnt lgkmcnt(3)
	v_mfma_f32_32x32x16_bf16 v[2:17], v[114:117], v[238:241], v[2:17]
	v_mfma_f32_32x32x16_bf16 v[18:33], v[114:117], v[246:249], v[18:33]
	s_waitcnt lgkmcnt(2)
	v_mfma_f32_32x32x16_bf16 v[34:49], v[118:121], v[238:241], v[34:49]
	v_mfma_f32_32x32x16_bf16 v[50:65], v[118:121], v[246:249], v[50:65]
	s_waitcnt lgkmcnt(1)
	v_mfma_f32_32x32x16_bf16 v[66:81], v[134:137], v[238:241], v[66:81]
	v_mfma_f32_32x32x16_bf16 v[82:97], v[134:137], v[246:249], v[82:97]
	s_waitcnt lgkmcnt(0)
	v_mfma_f32_32x32x16_bf16 v[98:113], v[138:141], v[238:241], v[98:113]
	v_mfma_f32_32x32x16_bf16 v[214:229], v[138:141], v[246:249], v[214:229]
	s_waitcnt vmcnt(0)
	s_barrier
	ds_read_b128 v[114:117], v142 offset:16384
	ds_read_b128 v[230:233], v144 offset:8192
	ds_read_b128 v[234:237], v144 offset:10240
	ds_read_b128 v[118:121], v142 offset:18432
	ds_read_b128 v[134:137], v142 offset:24576
	ds_read_b128 v[138:141], v142 offset:26624
	ds_read_b128 v[238:241], v145 offset:8192
	ds_read_b128 v[246:249], v145 offset:10240
	s_waitcnt lgkmcnt(6)
	v_mfma_f32_32x32x16_bf16 v[2:17], v[114:117], v[230:233], v[2:17]
	s_waitcnt lgkmcnt(5)
	v_mfma_f32_32x32x16_bf16 v[18:33], v[114:117], v[234:237], v[18:33]
	ds_read_b128 v[114:117], v143 offset:16384
	s_waitcnt lgkmcnt(5)
	v_mfma_f32_32x32x16_bf16 v[34:49], v[118:121], v[230:233], v[34:49]
	v_mfma_f32_32x32x16_bf16 v[50:65], v[118:121], v[234:237], v[50:65]
	ds_read_b128 v[118:121], v143 offset:18432
	s_waitcnt lgkmcnt(5)
	v_mfma_f32_32x32x16_bf16 v[66:81], v[134:137], v[230:233], v[66:81]
	v_mfma_f32_32x32x16_bf16 v[82:97], v[134:137], v[234:237], v[82:97]
	ds_read_b128 v[134:137], v143 offset:24576
	s_waitcnt lgkmcnt(5)
	v_mfma_f32_32x32x16_bf16 v[98:113], v[138:141], v[230:233], v[98:113]
	v_mfma_f32_32x32x16_bf16 v[214:229], v[138:141], v[234:237], v[214:229]
	ds_read_b128 v[138:141], v143 offset:26624
	s_waitcnt lgkmcnt(3)
	v_mfma_f32_32x32x16_bf16 v[2:17], v[114:117], v[238:241], v[2:17]
	v_mfma_f32_32x32x16_bf16 v[18:33], v[114:117], v[246:249], v[18:33]
	s_waitcnt lgkmcnt(2)
	v_mfma_f32_32x32x16_bf16 v[34:49], v[118:121], v[238:241], v[34:49]
	v_mfma_f32_32x32x16_bf16 v[50:65], v[118:121], v[246:249], v[50:65]
	s_waitcnt lgkmcnt(1)
	v_mfma_f32_32x32x16_bf16 v[66:81], v[134:137], v[238:241], v[66:81]
	v_mfma_f32_32x32x16_bf16 v[82:97], v[134:137], v[246:249], v[82:97]
	s_waitcnt lgkmcnt(0)
	v_mfma_f32_32x32x16_bf16 v[98:113], v[138:141], v[238:241], v[98:113]
	v_mfma_f32_32x32x16_bf16 v[214:229], v[138:141], v[246:249], v[214:229]
	s_nop 7
	s_nop 7
	s_barrier
; template <int AI>
; DI void gu_tile(char* wsb, int sub, int m0, int n0, char* lds) {
;     ...
;   const unsigned ib = (unsigned)((m0e + wa * 32 * AI + 4 * h) * 2816 + hc);
; #pragma unroll
;   for (int ai = 0; ai < AI; ++ai)
; #pragma unroll
;     for (int reg = 0; reg < 16; ++reg) {
;       float g = acc[ai][0][reg], u = acc[ai][1][reg];
;       float v = g * __builtin_amdgcn_rcpf(1.f + __expf(-g)) * u;
;       HIDu[ib + (unsigned)((ai * 32 + (reg & 3) + 8 * (reg >> 2)) * 2816)] = f2bf(v);
;       if ((reg & 7) == 7) __builtin_amdgcn_sched_barrier(0);
;     }
	v_mul_f32_e32 v250, 0xbfb8aa3b, v2
	v_mul_f32_e32 v251, 0xbfb8aa3b, v3
	v_exp_f32_e32 v250, v250
	v_exp_f32_e32 v251, v251
	v_add_u32_e32 v122, 0x0, v123
	v_add_f32_e32 v250, 1.0, v250
	v_add_f32_e32 v251, 1.0, v251
	v_rcp_f32_e32 v250, v250
	v_rcp_f32_e32 v251, v251
	s_nop 0
	v_mul_f32_e32 v250, v2, v250
	v_mul_f32_e32 v251, v3, v251
	v_mul_f32_e32 v250, v18, v250
	v_mul_f32_e32 v251, v19, v251
	s_nop 1
	v_mov_b32_dpp v252, v250 quad_perm:[1,0,3,2] row_mask:0xf bank_mask:0xf
	v_mov_b32_dpp v253, v251 quad_perm:[1,0,3,2] row_mask:0xf bank_mask:0xf
	v_cndmask_b32_e64 v254, v253, v250, s[46:47]
	v_cndmask_b32_e64 v255, v251, v252, s[46:47]
	v_cvt_pk_bf16_f32 v254, v254, v255
	global_store_dword v122, v254, s[34:35]
	v_mul_f32_e32 v250, 0xbfb8aa3b, v4
	v_mul_f32_e32 v251, 0xbfb8aa3b, v5
	v_exp_f32_e32 v250, v250
	v_exp_f32_e32 v251, v251
	v_add_u32_e32 v122, 0x2c00, v123
	v_add_f32_e32 v250, 1.0, v250
	v_add_f32_e32 v251, 1.0, v251
	v_rcp_f32_e32 v250, v250
	v_rcp_f32_e32 v251, v251
	s_nop 0
	v_mul_f32_e32 v250, v4, v250
	v_mul_f32_e32 v251, v5, v251
	v_mul_f32_e32 v250, v20, v250
	v_mul_f32_e32 v251, v21, v251
	s_nop 1
	v_mov_b32_dpp v252, v250 quad_perm:[1,0,3,2] row_mask:0xf bank_mask:0xf
	v_mov_b32_dpp v253, v251 quad_perm:[1,0,3,2] row_mask:0xf bank_mask:0xf
	v_cndmask_b32_e64 v254, v253, v250, s[46:47]
	v_cndmask_b32_e64 v255, v251, v252, s[46:47]
	v_cvt_pk_bf16_f32 v254, v254, v255
	global_store_dword v122, v254, s[34:35]
	v_mul_f32_e32 v250, 0xbfb8aa3b, v6
	v_mul_f32_e32 v251, 0xbfb8aa3b, v7
	v_exp_f32_e32 v250, v250
	v_exp_f32_e32 v251, v251
	v_add_u32_e32 v122, 0xb000, v123
	v_add_f32_e32 v250, 1.0, v250
	v_add_f32_e32 v251, 1.0, v251
	v_rcp_f32_e32 v250, v250
	v_rcp_f32_e32 v251, v251
	s_nop 0
	v_mul_f32_e32 v250, v6, v250
	v_mul_f32_e32 v251, v7, v251
	v_mul_f32_e32 v250, v22, v250
	v_mul_f32_e32 v251, v23, v251
	s_nop 1
	v_mov_b32_dpp v252, v250 quad_perm:[1,0,3,2] row_mask:0xf bank_mask:0xf
	v_mov_b32_dpp v253, v251 quad_perm:[1,0,3,2] row_mask:0xf bank_mask:0xf
	v_cndmask_b32_e64 v254, v253, v250, s[46:47]
	v_cndmask_b32_e64 v255, v251, v252, s[46:47]
	v_cvt_pk_bf16_f32 v254, v254, v255
	global_store_dword v122, v254, s[34:35]
	v_mul_f32_e32 v250, 0xbfb8aa3b, v8
	v_mul_f32_e32 v251, 0xbfb8aa3b, v9
	v_exp_f32_e32 v250, v250
	v_exp_f32_e32 v251, v251
	v_add_u32_e32 v122, 0xdc00, v123
	v_add_f32_e32 v250, 1.0, v250
	v_add_f32_e32 v251, 1.0, v251
	v_rcp_f32_e32 v250, v250
	v_rcp_f32_e32 v251, v251
	s_nop 0
	v_mul_f32_e32 v250, v8, v250
	v_mul_f32_e32 v251, v9, v251
	v_mul_f32_e32 v250, v24, v250
	v_mul_f32_e32 v251, v25, v251
	s_nop 1
	v_mov_b32_dpp v252, v250 quad_perm:[1,0,3,2] row_mask:0xf bank_mask:0xf
	v_mov_b32_dpp v253, v251 quad_perm:[1,0,3,2] row_mask:0xf bank_mask:0xf
	v_cndmask_b32_e64 v254, v253, v250, s[46:47]
	v_cndmask_b32_e64 v255, v251, v252, s[46:47]
	v_cvt_pk_bf16_f32 v254, v254, v255
	global_store_dword v122, v254, s[34:35]
	v_mul_f32_e32 v250, 0xbfb8aa3b, v10
	v_mul_f32_e32 v251, 0xbfb8aa3b, v11
	v_exp_f32_e32 v250, v250
	v_exp_f32_e32 v251, v251
	v_add_u32_e32 v122, 0x16000, v123
	v_add_f32_e32 v250, 1.0, v250
	v_add_f32_e32 v251, 1.0, v251
	v_rcp_f32_e32 v250, v250
	v_rcp_f32_e32 v251, v251
	s_nop 0
	v_mul_f32_e32 v250, v10, v250
	v_mul_f32_e32 v251, v11, v251
	v_mul_f32_e32 v250, v26, v250
	v_mul_f32_e32 v251, v27, v251
	s_nop 1
	v_mov_b32_dpp v252, v250 quad_perm:[1,0,3,2] row_mask:0xf bank_mask:0xf
	v_mov_b32_dpp v253, v251 quad_perm:[1,0,3,2] row_mask:0xf bank_mask:0xf
	v_cndmask_b32_e64 v254, v253, v250, s[46:47]
	v_cndmask_b32_e64 v255, v251, v252, s[46:47]
	v_cvt_pk_bf16_f32 v254, v254, v255
	global_store_dword v122, v254, s[34:35]
	v_mul_f32_e32 v250, 0xbfb8aa3b, v12
	v_mul_f32_e32 v251, 0xbfb8aa3b, v13
	v_exp_f32_e32 v250, v250
	v_exp_f32_e32 v251, v251
	v_add_u32_e32 v122, 0x18c00, v123
	v_add_f32_e32 v250, 1.0, v250
	v_add_f32_e32 v251, 1.0, v251
	v_rcp_f32_e32 v250, v250
	v_rcp_f32_e32 v251, v251
	s_nop 0
	v_mul_f32_e32 v250, v12, v250
	v_mul_f32_e32 v251, v13, v251
	v_mul_f32_e32 v250, v28, v250
	v_mul_f32_e32 v251, v29, v251
	s_nop 1
	v_mov_b32_dpp v252, v250 quad_perm:[1,0,3,2] row_mask:0xf bank_mask:0xf
	v_mov_b32_dpp v253, v251 quad_perm:[1,0,3,2] row_mask:0xf bank_mask:0xf
	v_cndmask_b32_e64 v254, v253, v250, s[46:47]
	v_cndmask_b32_e64 v255, v251, v252, s[46:47]
	v_cvt_pk_bf16_f32 v254, v254, v255
	global_store_dword v122, v254, s[34:35]
	v_mul_f32_e32 v250, 0xbfb8aa3b, v14
	v_mul_f32_e32 v251, 0xbfb8aa3b, v15
	v_exp_f32_e32 v250, v250
	v_exp_f32_e32 v251, v251
	v_add_u32_e32 v122, 0x21000, v123
	v_add_f32_e32 v250, 1.0, v250
	v_add_f32_e32 v251, 1.0, v251
	v_rcp_f32_e32 v250, v250
	v_rcp_f32_e32 v251, v251
	s_nop 0
	v_mul_f32_e32 v250, v14, v250
	v_mul_f32_e32 v251, v15, v251
	v_mul_f32_e32 v250, v30, v250
	v_mul_f32_e32 v251, v31, v251
	s_nop 1
	v_mov_b32_dpp v252, v250 quad_perm:[1,0,3,2] row_mask:0xf bank_mask:0xf
	v_mov_b32_dpp v253, v251 quad_perm:[1,0,3,2] row_mask:0xf bank_mask:0xf
	v_cndmask_b32_e64 v254, v253, v250, s[46:47]
	v_cndmask_b32_e64 v255, v251, v252, s[46:47]
	v_cvt_pk_bf16_f32 v254, v254, v255
	global_store_dword v122, v254, s[34:35]
	v_mul_f32_e32 v250, 0xbfb8aa3b, v16
	v_mul_f32_e32 v251, 0xbfb8aa3b, v17
	v_exp_f32_e32 v250, v250
	v_exp_f32_e32 v251, v251
	v_add_u32_e32 v122, 0x23c00, v123
	v_add_f32_e32 v250, 1.0, v250
	v_add_f32_e32 v251, 1.0, v251
	v_rcp_f32_e32 v250, v250
	v_rcp_f32_e32 v251, v251
	s_nop 0
	v_mul_f32_e32 v250, v16, v250
	v_mul_f32_e32 v251, v17, v251
	v_mul_f32_e32 v250, v32, v250
	v_mul_f32_e32 v251, v33, v251
	s_nop 1
	v_mov_b32_dpp v252, v250 quad_perm:[1,0,3,2] row_mask:0xf bank_mask:0xf
	v_mov_b32_dpp v253, v251 quad_perm:[1,0,3,2] row_mask:0xf bank_mask:0xf
; template <int AI>
; DI void gu_tile(char* wsb, int sub, int m0, int n0, char* lds) {
;     ...
;   const unsigned ib = (unsigned)((m0e + wa * 32 * AI + 4 * h) * 2816 + hc);
; #pragma unroll
;   for (int ai = 0; ai < AI; ++ai)
; #pragma unroll
;     for (int reg = 0; reg < 16; ++reg) {
;       float g = acc[ai][0][reg], u = acc[ai][1][reg];
;       float v = g * __builtin_amdgcn_rcpf(1.f + __expf(-g)) * u;
;       HIDu[ib + (unsigned)((ai * 32 + (reg & 3) + 8 * (reg >> 2)) * 2816)] = f2bf(v);
;       if ((reg & 7) == 7) __builtin_amdgcn_sched_barrier(0);
;     }
	v_cndmask_b32_e64 v254, v253, v250, s[46:47]
	v_cndmask_b32_e64 v255, v251, v252, s[46:47]
	v_cvt_pk_bf16_f32 v254, v254, v255
	global_store_dword v122, v254, s[34:35]
	v_mul_f32_e32 v250, 0xbfb8aa3b, v34
	v_mul_f32_e32 v251, 0xbfb8aa3b, v35
	v_exp_f32_e32 v250, v250
	v_exp_f32_e32 v251, v251
	v_add_u32_e32 v122, 0x2c000, v123
	v_add_f32_e32 v250, 1.0, v250
	v_add_f32_e32 v251, 1.0, v251
	v_rcp_f32_e32 v250, v250
	v_rcp_f32_e32 v251, v251
	s_nop 0
	v_mul_f32_e32 v250, v34, v250
	v_mul_f32_e32 v251, v35, v251
	v_mul_f32_e32 v250, v50, v250
	v_mul_f32_e32 v251, v51, v251
	s_nop 1
	v_mov_b32_dpp v252, v250 quad_perm:[1,0,3,2] row_mask:0xf bank_mask:0xf
	v_mov_b32_dpp v253, v251 quad_perm:[1,0,3,2] row_mask:0xf bank_mask:0xf
	v_cndmask_b32_e64 v254, v253, v250, s[46:47]
	v_cndmask_b32_e64 v255, v251, v252, s[46:47]
	v_cvt_pk_bf16_f32 v254, v254, v255
	global_store_dword v122, v254, s[34:35]
	v_mul_f32_e32 v250, 0xbfb8aa3b, v36
	v_mul_f32_e32 v251, 0xbfb8aa3b, v37
	v_exp_f32_e32 v250, v250
	v_exp_f32_e32 v251, v251
	v_add_u32_e32 v122, 0x2ec00, v123
	v_add_f32_e32 v250, 1.0, v250
	v_add_f32_e32 v251, 1.0, v251
	v_rcp_f32_e32 v250, v250
	v_rcp_f32_e32 v251, v251
	s_nop 0
	v_mul_f32_e32 v250, v36, v250
	v_mul_f32_e32 v251, v37, v251
	v_mul_f32_e32 v250, v52, v250
	v_mul_f32_e32 v251, v53, v251
	s_nop 1
	v_mov_b32_dpp v252, v250 quad_perm:[1,0,3,2] row_mask:0xf bank_mask:0xf
	v_mov_b32_dpp v253, v251 quad_perm:[1,0,3,2] row_mask:0xf bank_mask:0xf
	v_cndmask_b32_e64 v254, v253, v250, s[46:47]
	v_cndmask_b32_e64 v255, v251, v252, s[46:47]
	v_cvt_pk_bf16_f32 v254, v254, v255
	global_store_dword v122, v254, s[34:35]
	v_mul_f32_e32 v250, 0xbfb8aa3b, v38
	v_mul_f32_e32 v251, 0xbfb8aa3b, v39
	v_exp_f32_e32 v250, v250
	v_exp_f32_e32 v251, v251
	v_add_u32_e32 v122, 0x37000, v123
	v_add_f32_e32 v250, 1.0, v250
	v_add_f32_e32 v251, 1.0, v251
	v_rcp_f32_e32 v250, v250
	v_rcp_f32_e32 v251, v251
	s_nop 0
	v_mul_f32_e32 v250, v38, v250
	v_mul_f32_e32 v251, v39, v251
	v_mul_f32_e32 v250, v54, v250
	v_mul_f32_e32 v251, v55, v251
	s_nop 1
	v_mov_b32_dpp v252, v250 quad_perm:[1,0,3,2] row_mask:0xf bank_mask:0xf
	v_mov_b32_dpp v253, v251 quad_perm:[1,0,3,2] row_mask:0xf bank_mask:0xf
	v_cndmask_b32_e64 v254, v253, v250, s[46:47]
	v_cndmask_b32_e64 v255, v251, v252, s[46:47]
	v_cvt_pk_bf16_f32 v254, v254, v255
	global_store_dword v122, v254, s[34:35]
	v_mul_f32_e32 v250, 0xbfb8aa3b, v40
	v_mul_f32_e32 v251, 0xbfb8aa3b, v41
	v_exp_f32_e32 v250, v250
	v_exp_f32_e32 v251, v251
	v_add_u32_e32 v122, 0x39c00, v123
	v_add_f32_e32 v250, 1.0, v250
	v_add_f32_e32 v251, 1.0, v251
	v_rcp_f32_e32 v250, v250
	v_rcp_f32_e32 v251, v251
	s_nop 0
	v_mul_f32_e32 v250, v40, v250
	v_mul_f32_e32 v251, v41, v251
	v_mul_f32_e32 v250, v56, v250
	v_mul_f32_e32 v251, v57, v251
	s_nop 1
	v_mov_b32_dpp v252, v250 quad_perm:[1,0,3,2] row_mask:0xf bank_mask:0xf
	v_mov_b32_dpp v253, v251 quad_perm:[1,0,3,2] row_mask:0xf bank_mask:0xf
	v_cndmask_b32_e64 v254, v253, v250, s[46:47]
	v_cndmask_b32_e64 v255, v251, v252, s[46:47]
	v_cvt_pk_bf16_f32 v254, v254, v255
	global_store_dword v122, v254, s[34:35]
	v_mul_f32_e32 v250, 0xbfb8aa3b, v42
	v_mul_f32_e32 v251, 0xbfb8aa3b, v43
	v_exp_f32_e32 v250, v250
	v_exp_f32_e32 v251, v251
	v_add_u32_e32 v122, 0x42000, v123
	v_add_f32_e32 v250, 1.0, v250
	v_add_f32_e32 v251, 1.0, v251
	v_rcp_f32_e32 v250, v250
	v_rcp_f32_e32 v251, v251
	s_nop 0
	v_mul_f32_e32 v250, v42, v250
	v_mul_f32_e32 v251, v43, v251
	v_mul_f32_e32 v250, v58, v250
	v_mul_f32_e32 v251, v59, v251
	s_nop 1
	v_mov_b32_dpp v252, v250 quad_perm:[1,0,3,2] row_mask:0xf bank_mask:0xf
	v_mov_b32_dpp v253, v251 quad_perm:[1,0,3,2] row_mask:0xf bank_mask:0xf
	v_cndmask_b32_e64 v254, v253, v250, s[46:47]
	v_cndmask_b32_e64 v255, v251, v252, s[46:47]
	v_cvt_pk_bf16_f32 v254, v254, v255
	global_store_dword v122, v254, s[34:35]
	v_mul_f32_e32 v250, 0xbfb8aa3b, v44
	v_mul_f32_e32 v251, 0xbfb8aa3b, v45
	v_exp_f32_e32 v250, v250
	v_exp_f32_e32 v251, v251
	v_add_u32_e32 v122, 0x44c00, v123
	v_add_f32_e32 v250, 1.0, v250
	v_add_f32_e32 v251, 1.0, v251
	v_rcp_f32_e32 v250, v250
	v_rcp_f32_e32 v251, v251
	s_nop 0
	v_mul_f32_e32 v250, v44, v250
	v_mul_f32_e32 v251, v45, v251
	v_mul_f32_e32 v250, v60, v250
	v_mul_f32_e32 v251, v61, v251
	s_nop 1
	v_mov_b32_dpp v252, v250 quad_perm:[1,0,3,2] row_mask:0xf bank_mask:0xf
	v_mov_b32_dpp v253, v251 quad_perm:[1,0,3,2] row_mask:0xf bank_mask:0xf
	v_cndmask_b32_e64 v254, v253, v250, s[46:47]
	v_cndmask_b32_e64 v255, v251, v252, s[46:47]
	v_cvt_pk_bf16_f32 v254, v254, v255
	global_store_dword v122, v254, s[34:35]
	v_mul_f32_e32 v250, 0xbfb8aa3b, v46
	v_mul_f32_e32 v251, 0xbfb8aa3b, v47
	v_exp_f32_e32 v250, v250
	v_exp_f32_e32 v251, v251
	v_add_u32_e32 v122, 0x4d000, v123
	v_add_f32_e32 v250, 1.0, v250
	v_add_f32_e32 v251, 1.0, v251
	v_rcp_f32_e32 v250, v250
	v_rcp_f32_e32 v251, v251
	s_nop 0
	v_mul_f32_e32 v250, v46, v250
	v_mul_f32_e32 v251, v47, v251
	v_mul_f32_e32 v250, v62, v250
	v_mul_f32_e32 v251, v63, v251
	s_nop 1
	v_mov_b32_dpp v252, v250 quad_perm:[1,0,3,2] row_mask:0xf bank_mask:0xf
	v_mov_b32_dpp v253, v251 quad_perm:[1,0,3,2] row_mask:0xf bank_mask:0xf
	v_cndmask_b32_e64 v254, v253, v250, s[46:47]
	v_cndmask_b32_e64 v255, v251, v252, s[46:47]
	v_cvt_pk_bf16_f32 v254, v254, v255
	global_store_dword v122, v254, s[34:35]
	v_mul_f32_e32 v250, 0xbfb8aa3b, v48
	v_mul_f32_e32 v251, 0xbfb8aa3b, v49
	v_exp_f32_e32 v250, v250
	v_exp_f32_e32 v251, v251
	v_add_u32_e32 v122, 0x4fc00, v123
	v_add_f32_e32 v250, 1.0, v250
	v_add_f32_e32 v251, 1.0, v251
	v_rcp_f32_e32 v250, v250
	v_rcp_f32_e32 v251, v251
	s_nop 0
	v_mul_f32_e32 v250, v48, v250
	v_mul_f32_e32 v251, v49, v251
; template <int AI>
; DI void gu_tile(char* wsb, int sub, int m0, int n0, char* lds) {
;     ...
; #pragma unroll
;   for (int ai = 0; ai < AI; ++ai)
; #pragma unroll
;     for (int reg = 0; reg < 16; ++reg) {
;       float g = acc[ai][0][reg], u = acc[ai][1][reg];
;       float v = g * __builtin_amdgcn_rcpf(1.f + __expf(-g)) * u;
;       HIDu[ib + (unsigned)((ai * 32 + (reg & 3) + 8 * (reg >> 2)) * 2816)] = f2bf(v);
;       if ((reg & 7) == 7) __builtin_amdgcn_sched_barrier(0);
;     }
	v_mul_f32_e32 v250, v64, v250
	v_mul_f32_e32 v251, v65, v251
	s_nop 1
	v_mov_b32_dpp v252, v250 quad_perm:[1,0,3,2] row_mask:0xf bank_mask:0xf
	v_mov_b32_dpp v253, v251 quad_perm:[1,0,3,2] row_mask:0xf bank_mask:0xf
	v_cndmask_b32_e64 v254, v253, v250, s[46:47]
	v_cndmask_b32_e64 v255, v251, v252, s[46:47]
	v_cvt_pk_bf16_f32 v254, v254, v255
	global_store_dword v122, v254, s[34:35]
	v_mul_f32_e32 v250, 0xbfb8aa3b, v66
	v_mul_f32_e32 v251, 0xbfb8aa3b, v67
	v_exp_f32_e32 v250, v250
	v_exp_f32_e32 v251, v251
	v_add_u32_e32 v122, 0xb0000, v123
	v_add_f32_e32 v250, 1.0, v250
	v_add_f32_e32 v251, 1.0, v251
	v_rcp_f32_e32 v250, v250
	v_rcp_f32_e32 v251, v251
	s_nop 0
	v_mul_f32_e32 v250, v66, v250
	v_mul_f32_e32 v251, v67, v251
	v_mul_f32_e32 v250, v82, v250
	v_mul_f32_e32 v251, v83, v251
	s_nop 1
	v_mov_b32_dpp v252, v250 quad_perm:[1,0,3,2] row_mask:0xf bank_mask:0xf
	v_mov_b32_dpp v253, v251 quad_perm:[1,0,3,2] row_mask:0xf bank_mask:0xf
	v_cndmask_b32_e64 v254, v253, v250, s[46:47]
	v_cndmask_b32_e64 v255, v251, v252, s[46:47]
	v_cvt_pk_bf16_f32 v254, v254, v255
	global_store_dword v122, v254, s[34:35]
	v_mul_f32_e32 v250, 0xbfb8aa3b, v68
	v_mul_f32_e32 v251, 0xbfb8aa3b, v69
	v_exp_f32_e32 v250, v250
	v_exp_f32_e32 v251, v251
	v_add_u32_e32 v122, 0xb2c00, v123
	v_add_f32_e32 v250, 1.0, v250
	v_add_f32_e32 v251, 1.0, v251
	v_rcp_f32_e32 v250, v250
	v_rcp_f32_e32 v251, v251
	s_nop 0
	v_mul_f32_e32 v250, v68, v250
	v_mul_f32_e32 v251, v69, v251
	v_mul_f32_e32 v250, v84, v250
	v_mul_f32_e32 v251, v85, v251
	s_nop 1
	v_mov_b32_dpp v252, v250 quad_perm:[1,0,3,2] row_mask:0xf bank_mask:0xf
	v_mov_b32_dpp v253, v251 quad_perm:[1,0,3,2] row_mask:0xf bank_mask:0xf
	v_cndmask_b32_e64 v254, v253, v250, s[46:47]
	v_cndmask_b32_e64 v255, v251, v252, s[46:47]
	v_cvt_pk_bf16_f32 v254, v254, v255
	global_store_dword v122, v254, s[34:35]
	v_mul_f32_e32 v250, 0xbfb8aa3b, v70
	v_mul_f32_e32 v251, 0xbfb8aa3b, v71
	v_exp_f32_e32 v250, v250
	v_exp_f32_e32 v251, v251
	v_add_u32_e32 v122, 0xbb000, v123
	v_add_f32_e32 v250, 1.0, v250
	v_add_f32_e32 v251, 1.0, v251
	v_rcp_f32_e32 v250, v250
	v_rcp_f32_e32 v251, v251
	s_nop 0
	v_mul_f32_e32 v250, v70, v250
	v_mul_f32_e32 v251, v71, v251
	v_mul_f32_e32 v250, v86, v250
	v_mul_f32_e32 v251, v87, v251
	s_nop 1
	v_mov_b32_dpp v252, v250 quad_perm:[1,0,3,2] row_mask:0xf bank_mask:0xf
	v_mov_b32_dpp v253, v251 quad_perm:[1,0,3,2] row_mask:0xf bank_mask:0xf
	v_cndmask_b32_e64 v254, v253, v250, s[46:47]
	v_cndmask_b32_e64 v255, v251, v252, s[46:47]
	v_cvt_pk_bf16_f32 v254, v254, v255
	global_store_dword v122, v254, s[34:35]
	v_mul_f32_e32 v250, 0xbfb8aa3b, v72
	v_mul_f32_e32 v251, 0xbfb8aa3b, v73
	v_exp_f32_e32 v250, v250
	v_exp_f32_e32 v251, v251
	v_add_u32_e32 v122, 0xbdc00, v123
	v_add_f32_e32 v250, 1.0, v250
	v_add_f32_e32 v251, 1.0, v251
	v_rcp_f32_e32 v250, v250
	v_rcp_f32_e32 v251, v251
	s_nop 0
	v_mul_f32_e32 v250, v72, v250
	v_mul_f32_e32 v251, v73, v251
	v_mul_f32_e32 v250, v88, v250
	v_mul_f32_e32 v251, v89, v251
	s_nop 1
	v_mov_b32_dpp v252, v250 quad_perm:[1,0,3,2] row_mask:0xf bank_mask:0xf
	v_mov_b32_dpp v253, v251 quad_perm:[1,0,3,2] row_mask:0xf bank_mask:0xf
	v_cndmask_b32_e64 v254, v253, v250, s[46:47]
	v_cndmask_b32_e64 v255, v251, v252, s[46:47]
	v_cvt_pk_bf16_f32 v254, v254, v255
	global_store_dword v122, v254, s[34:35]
	v_mul_f32_e32 v250, 0xbfb8aa3b, v74
	v_mul_f32_e32 v251, 0xbfb8aa3b, v75
	v_exp_f32_e32 v250, v250
	v_exp_f32_e32 v251, v251
	v_add_u32_e32 v122, 0xc6000, v123
	v_add_f32_e32 v250, 1.0, v250
	v_add_f32_e32 v251, 1.0, v251
	v_rcp_f32_e32 v250, v250
	v_rcp_f32_e32 v251, v251
	s_nop 0
	v_mul_f32_e32 v250, v74, v250
	v_mul_f32_e32 v251, v75, v251
	v_mul_f32_e32 v250, v90, v250
	v_mul_f32_e32 v251, v91, v251
	s_nop 1
	v_mov_b32_dpp v252, v250 quad_perm:[1,0,3,2] row_mask:0xf bank_mask:0xf
	v_mov_b32_dpp v253, v251 quad_perm:[1,0,3,2] row_mask:0xf bank_mask:0xf
	v_cndmask_b32_e64 v254, v253, v250, s[46:47]
	v_cndmask_b32_e64 v255, v251, v252, s[46:47]
	v_cvt_pk_bf16_f32 v254, v254, v255
	global_store_dword v122, v254, s[34:35]
	v_mul_f32_e32 v250, 0xbfb8aa3b, v76
	v_mul_f32_e32 v251, 0xbfb8aa3b, v77
	v_exp_f32_e32 v250, v250
	v_exp_f32_e32 v251, v251
	v_add_u32_e32 v122, 0xc8c00, v123
	v_add_f32_e32 v250, 1.0, v250
	v_add_f32_e32 v251, 1.0, v251
	v_rcp_f32_e32 v250, v250
	v_rcp_f32_e32 v251, v251
	s_nop 0
	v_mul_f32_e32 v250, v76, v250
	v_mul_f32_e32 v251, v77, v251
	v_mul_f32_e32 v250, v92, v250
	v_mul_f32_e32 v251, v93, v251
	s_nop 1
	v_mov_b32_dpp v252, v250 quad_perm:[1,0,3,2] row_mask:0xf bank_mask:0xf
	v_mov_b32_dpp v253, v251 quad_perm:[1,0,3,2] row_mask:0xf bank_mask:0xf
	v_cndmask_b32_e64 v254, v253, v250, s[46:47]
	v_cndmask_b32_e64 v255, v251, v252, s[46:47]
	v_cvt_pk_bf16_f32 v254, v254, v255
	global_store_dword v122, v254, s[34:35]
	v_mul_f32_e32 v250, 0xbfb8aa3b, v78
	v_mul_f32_e32 v251, 0xbfb8aa3b, v79
	v_exp_f32_e32 v250, v250
	v_exp_f32_e32 v251, v251
	v_add_u32_e32 v122, 0xd1000, v123
	v_add_f32_e32 v250, 1.0, v250
	v_add_f32_e32 v251, 1.0, v251
	v_rcp_f32_e32 v250, v250
	v_rcp_f32_e32 v251, v251
	s_nop 0
	v_mul_f32_e32 v250, v78, v250
	v_mul_f32_e32 v251, v79, v251
	v_mul_f32_e32 v250, v94, v250
	v_mul_f32_e32 v251, v95, v251
	s_nop 1
	v_mov_b32_dpp v252, v250 quad_perm:[1,0,3,2] row_mask:0xf bank_mask:0xf
	v_mov_b32_dpp v253, v251 quad_perm:[1,0,3,2] row_mask:0xf bank_mask:0xf
	v_cndmask_b32_e64 v254, v253, v250, s[46:47]
	v_cndmask_b32_e64 v255, v251, v252, s[46:47]
	v_cvt_pk_bf16_f32 v254, v254, v255
	global_store_dword v122, v254, s[34:35]
	v_mul_f32_e32 v250, 0xbfb8aa3b, v80
	v_mul_f32_e32 v251, 0xbfb8aa3b, v81
	v_exp_f32_e32 v250, v250
	v_exp_f32_e32 v251, v251
; template <int AI>
; DI void gu_tile(char* wsb, int sub, int m0, int n0, char* lds) {
;     ...
; #pragma unroll
;   for (int ai = 0; ai < AI; ++ai)
; #pragma unroll
;     for (int reg = 0; reg < 16; ++reg) {
;       float g = acc[ai][0][reg], u = acc[ai][1][reg];
;       float v = g * __builtin_amdgcn_rcpf(1.f + __expf(-g)) * u;
;       HIDu[ib + (unsigned)((ai * 32 + (reg & 3) + 8 * (reg >> 2)) * 2816)] = f2bf(v);
;       if ((reg & 7) == 7) __builtin_amdgcn_sched_barrier(0);
;     }
; }
; DI void phase_gu(const Params& p, char* wsb, int sub, int mrows, char* lds) {
;   int mt, nt;
;   for (int rnd = 0; next_tile(rnd, 128, 44, mt, nt); ++rnd) gu_tile<2>(wsb, sub, mt * 128, nt * 128, lds);
;   if (mrows > TL)
;     for (int rnd = 0; next_tile(rnd, 32, 44, mt, nt); ++rnd) gu_tile<1>(wsb, sub, TL + mt * 64, nt * 128, lds);
	v_add_u32_e32 v122, 0xd3c00, v123
	v_add_f32_e32 v250, 1.0, v250
	v_add_f32_e32 v251, 1.0, v251
	v_rcp_f32_e32 v250, v250
	v_rcp_f32_e32 v251, v251
	s_nop 0
	v_mul_f32_e32 v250, v80, v250
	v_mul_f32_e32 v251, v81, v251
	v_mul_f32_e32 v250, v96, v250
	v_mul_f32_e32 v251, v97, v251
	s_nop 1
	v_mov_b32_dpp v252, v250 quad_perm:[1,0,3,2] row_mask:0xf bank_mask:0xf
	v_mov_b32_dpp v253, v251 quad_perm:[1,0,3,2] row_mask:0xf bank_mask:0xf
	v_cndmask_b32_e64 v254, v253, v250, s[46:47]
	v_cndmask_b32_e64 v255, v251, v252, s[46:47]
	v_cvt_pk_bf16_f32 v254, v254, v255
	global_store_dword v122, v254, s[34:35]
	v_mul_f32_e32 v250, 0xbfb8aa3b, v98
	v_mul_f32_e32 v251, 0xbfb8aa3b, v99
	v_exp_f32_e32 v250, v250
	v_exp_f32_e32 v251, v251
	v_add_u32_e32 v122, 0xdc000, v123
	v_add_f32_e32 v250, 1.0, v250
	v_add_f32_e32 v251, 1.0, v251
	v_rcp_f32_e32 v250, v250
	v_rcp_f32_e32 v251, v251
	s_nop 0
	v_mul_f32_e32 v250, v98, v250
	v_mul_f32_e32 v251, v99, v251
	v_mul_f32_e32 v250, v214, v250
	v_mul_f32_e32 v251, v215, v251
	s_nop 1
	v_mov_b32_dpp v252, v250 quad_perm:[1,0,3,2] row_mask:0xf bank_mask:0xf
	v_mov_b32_dpp v253, v251 quad_perm:[1,0,3,2] row_mask:0xf bank_mask:0xf
	v_cndmask_b32_e64 v254, v253, v250, s[46:47]
	v_cndmask_b32_e64 v255, v251, v252, s[46:47]
	v_cvt_pk_bf16_f32 v254, v254, v255
	global_store_dword v122, v254, s[34:35]
	v_mul_f32_e32 v250, 0xbfb8aa3b, v100
	v_mul_f32_e32 v251, 0xbfb8aa3b, v101
	v_exp_f32_e32 v250, v250
	v_exp_f32_e32 v251, v251
	v_add_u32_e32 v122, 0xdec00, v123
	v_add_f32_e32 v250, 1.0, v250
	v_add_f32_e32 v251, 1.0, v251
	v_rcp_f32_e32 v250, v250
	v_rcp_f32_e32 v251, v251
	s_nop 0
	v_mul_f32_e32 v250, v100, v250
	v_mul_f32_e32 v251, v101, v251
	v_mul_f32_e32 v250, v216, v250
	v_mul_f32_e32 v251, v217, v251
	s_nop 1
	v_mov_b32_dpp v252, v250 quad_perm:[1,0,3,2] row_mask:0xf bank_mask:0xf
	v_mov_b32_dpp v253, v251 quad_perm:[1,0,3,2] row_mask:0xf bank_mask:0xf
	v_cndmask_b32_e64 v254, v253, v250, s[46:47]
	v_cndmask_b32_e64 v255, v251, v252, s[46:47]
	v_cvt_pk_bf16_f32 v254, v254, v255
	global_store_dword v122, v254, s[34:35]
	v_mul_f32_e32 v250, 0xbfb8aa3b, v102
	v_mul_f32_e32 v251, 0xbfb8aa3b, v103
	v_exp_f32_e32 v250, v250
	v_exp_f32_e32 v251, v251
	v_add_u32_e32 v122, 0xe7000, v123
	v_add_f32_e32 v250, 1.0, v250
	v_add_f32_e32 v251, 1.0, v251
	v_rcp_f32_e32 v250, v250
	v_rcp_f32_e32 v251, v251
	s_nop 0
	v_mul_f32_e32 v250, v102, v250
	v_mul_f32_e32 v251, v103, v251
	v_mul_f32_e32 v250, v218, v250
	v_mul_f32_e32 v251, v219, v251
	s_nop 1
	v_mov_b32_dpp v252, v250 quad_perm:[1,0,3,2] row_mask:0xf bank_mask:0xf
	v_mov_b32_dpp v253, v251 quad_perm:[1,0,3,2] row_mask:0xf bank_mask:0xf
	v_cndmask_b32_e64 v254, v253, v250, s[46:47]
	v_cndmask_b32_e64 v255, v251, v252, s[46:47]
	v_cvt_pk_bf16_f32 v254, v254, v255
	global_store_dword v122, v254, s[34:35]
	v_mul_f32_e32 v250, 0xbfb8aa3b, v104
	v_mul_f32_e32 v251, 0xbfb8aa3b, v105
	v_exp_f32_e32 v250, v250
	v_exp_f32_e32 v251, v251
	v_add_u32_e32 v122, 0xe9c00, v123
	v_add_f32_e32 v250, 1.0, v250
	v_add_f32_e32 v251, 1.0, v251
	v_rcp_f32_e32 v250, v250
	v_rcp_f32_e32 v251, v251
	s_nop 0
	v_mul_f32_e32 v250, v104, v250
	v_mul_f32_e32 v251, v105, v251
	v_mul_f32_e32 v250, v220, v250
	v_mul_f32_e32 v251, v221, v251
	s_nop 1
	v_mov_b32_dpp v252, v250 quad_perm:[1,0,3,2] row_mask:0xf bank_mask:0xf
	v_mov_b32_dpp v253, v251 quad_perm:[1,0,3,2] row_mask:0xf bank_mask:0xf
	v_cndmask_b32_e64 v254, v253, v250, s[46:47]
	v_cndmask_b32_e64 v255, v251, v252, s[46:47]
	v_cvt_pk_bf16_f32 v254, v254, v255
	global_store_dword v122, v254, s[34:35]
	v_mul_f32_e32 v250, 0xbfb8aa3b, v106
	v_mul_f32_e32 v251, 0xbfb8aa3b, v107
	v_exp_f32_e32 v250, v250
	v_exp_f32_e32 v251, v251
	v_add_u32_e32 v122, 0xf2000, v123
	v_add_f32_e32 v250, 1.0, v250
	v_add_f32_e32 v251, 1.0, v251
	v_rcp_f32_e32 v250, v250
	v_rcp_f32_e32 v251, v251
	s_nop 0
	v_mul_f32_e32 v250, v106, v250
	v_mul_f32_e32 v251, v107, v251
	v_mul_f32_e32 v250, v222, v250
	v_mul_f32_e32 v251, v223, v251
	s_nop 1
	v_mov_b32_dpp v252, v250 quad_perm:[1,0,3,2] row_mask:0xf bank_mask:0xf
	v_mov_b32_dpp v253, v251 quad_perm:[1,0,3,2] row_mask:0xf bank_mask:0xf
	v_cndmask_b32_e64 v254, v253, v250, s[46:47]
	v_cndmask_b32_e64 v255, v251, v252, s[46:47]
	v_cvt_pk_bf16_f32 v254, v254, v255
	global_store_dword v122, v254, s[34:35]
	v_mul_f32_e32 v250, 0xbfb8aa3b, v108
	v_mul_f32_e32 v251, 0xbfb8aa3b, v109
	v_exp_f32_e32 v250, v250
	v_exp_f32_e32 v251, v251
	v_add_u32_e32 v122, 0xf4c00, v123
	v_add_f32_e32 v250, 1.0, v250
	v_add_f32_e32 v251, 1.0, v251
	v_rcp_f32_e32 v250, v250
	v_rcp_f32_e32 v251, v251
	s_nop 0
	v_mul_f32_e32 v250, v108, v250
	v_mul_f32_e32 v251, v109, v251
	v_mul_f32_e32 v250, v224, v250
	v_mul_f32_e32 v251, v225, v251
	s_nop 1
	v_mov_b32_dpp v252, v250 quad_perm:[1,0,3,2] row_mask:0xf bank_mask:0xf
	v_mov_b32_dpp v253, v251 quad_perm:[1,0,3,2] row_mask:0xf bank_mask:0xf
	v_cndmask_b32_e64 v254, v253, v250, s[46:47]
	v_cndmask_b32_e64 v255, v251, v252, s[46:47]
	v_cvt_pk_bf16_f32 v254, v254, v255
	global_store_dword v122, v254, s[34:35]
	v_mul_f32_e32 v250, 0xbfb8aa3b, v110
	v_mul_f32_e32 v251, 0xbfb8aa3b, v111
	v_exp_f32_e32 v250, v250
	v_exp_f32_e32 v251, v251
	v_add_u32_e32 v122, 0xfd000, v123
	v_add_f32_e32 v250, 1.0, v250
	v_add_f32_e32 v251, 1.0, v251
	v_rcp_f32_e32 v250, v250
	v_rcp_f32_e32 v251, v251
	s_nop 0
	v_mul_f32_e32 v250, v110, v250
	v_mul_f32_e32 v251, v111, v251
	v_mul_f32_e32 v250, v226, v250
	v_mul_f32_e32 v251, v227, v251
	s_nop 1
	v_mov_b32_dpp v252, v250 quad_perm:[1,0,3,2] row_mask:0xf bank_mask:0xf
	v_mov_b32_dpp v253, v251 quad_perm:[1,0,3,2] row_mask:0xf bank_mask:0xf
	v_cndmask_b32_e64 v254, v253, v250, s[46:47]
	v_cndmask_b32_e64 v255, v251, v252, s[46:47]
	v_cvt_pk_bf16_f32 v254, v254, v255
	global_store_dword v122, v254, s[34:35]
	v_mul_f32_e32 v250, 0xbfb8aa3b, v112
	v_mul_f32_e32 v251, 0xbfb8aa3b, v113
	v_exp_f32_e32 v250, v250
	v_exp_f32_e32 v251, v251
	v_add_u32_e32 v122, 0xffc00, v123
	v_add_f32_e32 v250, 1.0, v250
	v_add_f32_e32 v251, 1.0, v251
	v_rcp_f32_e32 v250, v250
	v_rcp_f32_e32 v251, v251
	s_nop 0
	v_mul_f32_e32 v250, v112, v250
	v_mul_f32_e32 v251, v113, v251
	v_mul_f32_e32 v250, v228, v250
	v_mul_f32_e32 v251, v229, v251
	s_nop 1
	v_mov_b32_dpp v252, v250 quad_perm:[1,0,3,2] row_mask:0xf bank_mask:0xf
	v_mov_b32_dpp v253, v251 quad_perm:[1,0,3,2] row_mask:0xf bank_mask:0xf
	v_cndmask_b32_e64 v254, v253, v250, s[46:47]
	v_cndmask_b32_e64 v255, v251, v252, s[46:47]
	v_cvt_pk_bf16_f32 v254, v254, v255
	global_store_dword v122, v254, s[34:35]
	s_add_u32 s32, s32, 1
	s_cmp_lt_u32 s32, 5
	s_cbranch_scc1 .Lgu1_round
	s_lshr_b32 s37, s40, 4
	s_add_u32 s37, s37, 40
	s_and_b32 s50, s40, 15
	s_lshl_b32 s51, s41, 4
	s_add_u32 s50, s50, s51
	s_lshr_b32 s51, s50, 3
	s_mul_i32 s51, s51, 0x160
	s_lshl_b32 s52, s37, 3
	s_add_u32 s51, s51, s52
	s_and_b32 s52, s50, 7
	s_add_u32 s14, s51, s52
	s_lshl_b32 s15, s14, 7
	s_mov_b32 s52, 1
	v_writelane_b32 v245, s52, 0

; #define TIDX opaque_tid()
; #define GAS __attribute__((address_space(1)))
; DI int opaque0() { int z = 0; asm volatile("" : "+v"(z)); return z; }
; template <int AI>
; DI void gu_tile(char* wsb, int sub, int m0, int n0, char* lds) {
;   const u16* H = (const u16*)(wsb + OFF_H);
;   const u16* W = (const u16*)(wsb + OFF_W) + (sub ? W_GU1 : W_GU0);
;   u16* HID = (u16*)(wsb + OFF_HID);
;   const int lane = TIDX & 63, wid = TIDX >> 6, wa = wid >> 1, wb = wid & 1, r = lane & 31, h = lane >> 5;
;   f32x16 acc[AI][2]; zero_acc<AI, 2>(acc);
;   gemm_tile<AI, 2>(H + (size_t)m0 * 1024, 1024, W + (size_t)n0 * 1024, 1024, 16, false, acc, lds);
;   const int m0e = m0 + opaque0();
;   const int hc = (n0 >> 1) + wb * 32 + r;
;   GAS u16* HIDu = uptr(HID);
;   const unsigned ib = (unsigned)((m0e + wa * 32 * AI + 4 * h) * 2816 + hc);
.LBB0_1204:
	s_or_b64 exec, exec, s[6:7]
	s_mov_b32 s6, s19
	s_mov_b64 s[8:9], s[20:21]
	s_waitcnt lgkmcnt(0)
	s_barrier
	s_mov_b64 s[14:15], s[26:27]
	s_add_u32 s8, s14, s6
	v_readlane_b32 s6, v242, 3
	v_readlane_b32 s7, v242, 4
	s_addc_u32 s9, s15, 0
	s_and_b64 vcc, exec, s[6:7]
	s_mov_b64 s[10:11], s[22:23]
	s_mov_b64 s[12:13], s[24:25]
	s_cbranch_vccnz .LBB0_1208
	s_add_u32 s10, s8, 0x77b7000
	s_addc_u32 s11, s9, 0
	s_add_u32 s12, s8, 0x1d537000
	s_addc_u32 s13, s9, 0
	s_add_u32 s6, s8, 0x9bb7000
	s_addc_u32 s7, s9, 0
	v_readlane_b32 s14, v243, 18
	v_readlane_b32 s15, v243, 5
	v_readlane_b32 s53, v243, 6
	v_readlane_b32 s56, v243, 7
	s_mov_b32 s57, 0x1ffffc0
	s_movk_i32 s64, 0xb00
	s_mov_b64 s[66:67], 0x200
	s_mov_b64 s[68:69], 0x80
	s_mov_b64 s[70:71], 0x180
	s_mov_b64 s[72:73], 0x280
	s_mov_b64 s[74:75], 0x300
	s_mov_b64 s[76:77], 0x380
	s_mov_b64 s[80:81], 0x400
	s_mov_b64 s[82:83], 0x480
	s_mov_b64 s[84:85], 0x500
	s_mov_b64 s[88:89], 0x580
	s_mov_b64 vcc, 0x600
	s_waitcnt vmcnt(0)
	s_cmpk_lg_u32 s92, 0x200
	s_cbranch_scc1 .LBB0_1206
	v_and_b32_e32 v0, 31, v178
	v_bfe_u32 v122, v178, 5, 1
	v_bfe_u32 v123, v178, 2, 2
	v_xor_b32_e32 v122, v122, v123
	v_lshlrev_b32_e32 v122, 4, v122
	v_bfe_u32 v123, v178, 7, 1
	v_lshl_add_u32 v123, v123, 6, v0
	v_lshl_add_u32 v142, v123, 6, v122
	v_xor_b32_e32 v143, 32, v142
	v_bfe_u32 v123, v178, 6, 1
	v_lshl_add_u32 v123, v123, 6, v0
	v_lshl_add_u32 v144, v123, 6, v122
	v_add_u32_e32 v144, 0xc000, v144
	v_xor_b32_e32 v145, 32, v144
	v_bfe_u32 v122, v178, 7, 1
	v_lshlrev_b32_e32 v122, 6, v122
	v_bfe_u32 v123, v178, 5, 1
	v_lshl_add_u32 v122, v123, 2, v122
	v_mul_u32_u24_e32 v122, 0xb00, v122
	v_bfe_u32 v123, v178, 6, 1
	v_lshl_add_u32 v123, v123, 5, v0
	v_add_u32_e32 v122, v122, v123
	v_lshlrev_b32_e32 v124, 1, v122
	v_lshrrev_b32_e32 v0, 2, v178
	v_bfe_u32 v122, v178, 4, 2
	v_and_b32_e32 v123, 3, v178
	v_xor_b32_e32 v122, v122, v123
	v_lshlrev_b32_e32 v122, 4, v122
	v_lshl_add_u32 v126, v0, 11, v122
	v_add_u32_e32 v127, 0x20000, v126
	v_add_u32_e32 v128, 0x40000, v126
	v_add_u32_e32 v129, 0x60000, v126
	v_lshrrev_b32_e32 v0, 6, v178
	s_nop 1
	v_readfirstlane_b32 s18, v0
	s_lshl_b32 s18, s18, 10
	s_and_b32 s41, s96, 7
	s_lshr_b32 s40, s96, 3
	s_mov_b32 s32, 0
	s_mov_b32 s46, 0x55555555
	s_mov_b32 s47, 0x55555555
	v_and_b32_e32 v123, 1, v178
	v_mul_u32_u24_e32 v123, 0x15fe, v123
	v_add_u32_e32 v123, v123, v124
